# final LayerNorm: g/b loaded once per wave, all eight row chunks in flight with counted vmcnt instead of vmcnt(0) per chunk
# speedup vs baseline: 1.0005x; 1.0005x over previous
.LBB0_1329:
	s_load_dwordx8 s[4:11], s[2:3], 0x60
	v_ashrrev_i32_e32 v3, 31, v2
	v_lshlrev_b64 v[22:23], 4, v[2:3]
	s_mov_b64 s[2:3], 0xe000
	s_ashr_i32 s1, s0, 31
	s_waitcnt lgkmcnt(0)
	v_lshl_add_u64 v[18:19], s[4:5], 0, v[22:23]
	v_lshl_add_u64 v[20:21], s[6:7], 0, v[22:23]
	v_lshl_add_u64 v[2:3], v[18:19], 0, s[2:3]
	v_lshl_add_u64 v[4:5], v[20:21], 0, s[2:3]
	s_mov_b64 s[2:3], 0xf000
	s_waitcnt vmcnt(4)
	v_lshl_add_u64 v[6:7], v[18:19], 0, s[2:3]
	v_lshl_add_u64 v[8:9], v[20:21], 0, s[2:3]
	s_mov_b64 s[2:3], 0xf400
	v_lshl_add_u64 v[10:11], v[18:19], 0, s[2:3]
	v_lshl_add_u64 v[12:13], v[20:21], 0, s[2:3]
	s_mov_b64 s[2:3], 0xf800
	v_lshl_add_u64 v[14:15], v[18:19], 0, s[2:3]
	v_lshl_add_u64 v[16:17], v[20:21], 0, s[2:3]
	s_mov_b64 s[2:3], 0xfc00
	v_lshl_add_u64 v[18:19], v[18:19], 0, s[2:3]
	v_lshl_add_u64 v[20:21], v[20:21], 0, s[2:3]
	s_lshl_b64 s[2:3], s[0:1], 13
	s_add_u32 s2, s8, s2
	s_addc_u32 s3, s9, s3
	v_lshl_add_u64 v[22:23], s[2:3], 0, v[22:23]
	s_mov_b64 s[2:3], 0x1000
	v_lshl_add_u64 v[22:23], v[22:23], 0, s[2:3]
	s_lshl_b64 s[2:3], s[0:1], 3
	v_readlane_b32 s4, v254, 34
	v_readlane_b32 s5, v254, 35
	s_add_u32 s1, s4, s2
	s_addc_u32 s2, s5, s3
	s_add_u32 s4, s10, s1
	s_addc_u32 s5, s11, s2
	v_readlane_b32 s8, v254, 28
	v_readlane_b32 s10, v254, 32
	v_readlane_b32 s6, v254, 30
	v_readlane_b32 s9, v254, 29
	v_readlane_b32 s11, v254, 33
	v_readlane_b32 s7, v254, 31
	global_load_dwordx4 v[40:43], v[2:3], off
	global_load_dwordx4 v[44:47], v[4:5], off
	global_load_dwordx4 v[48:51], v[2:3], off offset:1024
	global_load_dwordx4 v[52:55], v[4:5], off offset:1024
	global_load_dwordx4 v[56:59], v[2:3], off offset:2048
	global_load_dwordx4 v[60:63], v[4:5], off offset:2048
	global_load_dwordx4 v[64:67], v[2:3], off offset:3072
	global_load_dwordx4 v[68:71], v[4:5], off offset:3072
	global_load_dwordx4 v[72:75], v[6:7], off
	global_load_dwordx4 v[76:79], v[8:9], off
	global_load_dwordx4 v[80:83], v[10:11], off
	global_load_dwordx4 v[84:87], v[12:13], off
	global_load_dwordx4 v[88:91], v[14:15], off
	global_load_dwordx4 v[92:95], v[16:17], off
	global_load_dwordx4 v[96:99], v[18:19], off
	global_load_dwordx4 v[100:103], v[20:21], off
.LBB0_1330:
	s_mov_b32 s2, 0x3a000000
	global_load_dwordx2 v[24:25], v211, s[4:5]
	global_load_dwordx4 v[104:107], v[22:23], off offset:-4096
	global_load_dwordx4 v[108:111], v[22:23], off offset:-3072
	global_load_dwordx4 v[112:115], v[22:23], off offset:-2048
	global_load_dwordx4 v[116:119], v[22:23], off offset:-1024
	global_load_dwordx4 v[120:123], v[22:23], off offset:0
	global_load_dwordx4 v[124:127], v[22:23], off offset:1024
	global_load_dwordx4 v[128:131], v[22:23], off offset:2048
	global_load_dwordx4 v[132:135], v[22:23], off offset:3072
	s_add_i32 s0, s0, s6
	s_add_u32 s4, s4, s10
	s_addc_u32 s5, s5, s11
	s_cmpk_gt_i32 s0, 0x3fff
	s_waitcnt vmcnt(8)
	v_pk_mul_f32 v[24:25], s[2:3], v[24:25] op_sel_hi:[0,1]
	v_fma_f32 v1, -v24, v24, v25
	v_add_f32_e32 v1, 0x3727c5ac, v1
	v_rsq_f32_e32 v26, v1
	s_waitcnt vmcnt(7)
	v_sub_f32_e32 v104, v104, v24
	v_sub_f32_e32 v105, v105, v24
	v_sub_f32_e32 v106, v106, v24
	v_sub_f32_e32 v107, v107, v24
	v_pk_mul_f32 v[104:105], v[26:27], v[104:105] op_sel_hi:[0,1]
	v_pk_mul_f32 v[106:107], v[26:27], v[106:107] op_sel_hi:[0,1]
	v_pk_fma_f32 v[104:105], v[40:41], v[104:105], v[44:45]
	v_pk_fma_f32 v[106:107], v[42:43], v[106:107], v[46:47]
	global_store_dwordx4 v[22:23], v[104:107], off offset:-4096
	s_waitcnt vmcnt(7)
	v_sub_f32_e32 v108, v108, v24
	v_sub_f32_e32 v109, v109, v24
	v_sub_f32_e32 v110, v110, v24
	v_sub_f32_e32 v111, v111, v24
	v_pk_mul_f32 v[108:109], v[26:27], v[108:109] op_sel_hi:[0,1]
	v_pk_mul_f32 v[110:111], v[26:27], v[110:111] op_sel_hi:[0,1]
	v_pk_fma_f32 v[108:109], v[48:49], v[108:109], v[52:53]
	v_pk_fma_f32 v[110:111], v[50:51], v[110:111], v[54:55]
	global_store_dwordx4 v[22:23], v[108:111], off offset:-3072
	s_waitcnt vmcnt(7)
	v_sub_f32_e32 v112, v112, v24
	v_sub_f32_e32 v113, v113, v24
	v_sub_f32_e32 v114, v114, v24
	v_sub_f32_e32 v115, v115, v24
	v_pk_mul_f32 v[112:113], v[26:27], v[112:113] op_sel_hi:[0,1]
	v_pk_mul_f32 v[114:115], v[26:27], v[114:115] op_sel_hi:[0,1]
	v_pk_fma_f32 v[112:113], v[56:57], v[112:113], v[60:61]
	v_pk_fma_f32 v[114:115], v[58:59], v[114:115], v[62:63]
	global_store_dwordx4 v[22:23], v[112:115], off offset:-2048
	s_waitcnt vmcnt(7)
	v_sub_f32_e32 v116, v116, v24
	v_sub_f32_e32 v117, v117, v24
	v_sub_f32_e32 v118, v118, v24
	v_sub_f32_e32 v119, v119, v24
	v_pk_mul_f32 v[116:117], v[26:27], v[116:117] op_sel_hi:[0,1]
	v_pk_mul_f32 v[118:119], v[26:27], v[118:119] op_sel_hi:[0,1]
	v_pk_fma_f32 v[116:117], v[64:65], v[116:117], v[68:69]
	v_pk_fma_f32 v[118:119], v[66:67], v[118:119], v[70:71]
	global_store_dwordx4 v[22:23], v[116:119], off offset:-1024
	s_waitcnt vmcnt(7)
	v_sub_f32_e32 v120, v120, v24
	v_sub_f32_e32 v121, v121, v24
	v_sub_f32_e32 v122, v122, v24
	v_sub_f32_e32 v123, v123, v24
	v_pk_mul_f32 v[120:121], v[26:27], v[120:121] op_sel_hi:[0,1]
	v_pk_mul_f32 v[122:123], v[26:27], v[122:123] op_sel_hi:[0,1]
	v_pk_fma_f32 v[120:121], v[72:73], v[120:121], v[76:77]
	v_pk_fma_f32 v[122:123], v[74:75], v[122:123], v[78:79]
	global_store_dwordx4 v[22:23], v[120:123], off offset:0
	s_waitcnt vmcnt(7)
	v_sub_f32_e32 v124, v124, v24
	v_sub_f32_e32 v125, v125, v24
	v_sub_f32_e32 v126, v126, v24
	v_sub_f32_e32 v127, v127, v24
	v_pk_mul_f32 v[124:125], v[26:27], v[124:125] op_sel_hi:[0,1]
	v_pk_mul_f32 v[126:127], v[26:27], v[126:127] op_sel_hi:[0,1]
	v_pk_fma_f32 v[124:125], v[80:81], v[124:125], v[84:85]
	v_pk_fma_f32 v[126:127], v[82:83], v[126:127], v[86:87]
	global_store_dwordx4 v[22:23], v[124:127], off offset:1024
	s_waitcnt vmcnt(7)
	v_sub_f32_e32 v128, v128, v24
	v_sub_f32_e32 v129, v129, v24
	v_sub_f32_e32 v130, v130, v24
	v_sub_f32_e32 v131, v131, v24
	v_pk_mul_f32 v[128:129], v[26:27], v[128:129] op_sel_hi:[0,1]
	v_pk_mul_f32 v[130:131], v[26:27], v[130:131] op_sel_hi:[0,1]
	v_pk_fma_f32 v[128:129], v[88:89], v[128:129], v[92:93]
	v_pk_fma_f32 v[130:131], v[90:91], v[130:131], v[94:95]
	global_store_dwordx4 v[22:23], v[128:131], off offset:2048
	s_waitcnt vmcnt(7)
	v_sub_f32_e32 v132, v132, v24
	v_sub_f32_e32 v133, v133, v24
	v_sub_f32_e32 v134, v134, v24
	v_sub_f32_e32 v135, v135, v24
	v_pk_mul_f32 v[132:133], v[26:27], v[132:133] op_sel_hi:[0,1]
	v_pk_mul_f32 v[134:135], v[26:27], v[134:135] op_sel_hi:[0,1]
	v_pk_fma_f32 v[132:133], v[96:97], v[132:133], v[100:101]
	v_pk_fma_f32 v[134:135], v[98:99], v[134:135], v[102:103]
	global_store_dwordx4 v[22:23], v[132:135], off offset:3072
	v_lshl_add_u64 v[22:23], v[22:23], 0, s[8:9]
	s_cbranch_scc0 .LBB0_1330
	s_getpc_b64 s[98:99]
